# rmsnorm+modulate phases rewritten by hand: gain vector loaded once per wave, shift/scale once per row pair, next row pair prefetched during reduction/epilogue, counted vmcnt
# speedup vs baseline: 1.0228x; 1.0162x over previous
.LBB0_182:
	s_or_b64 exec, exec, s[0:1]
	s_waitcnt lgkmcnt(0)
	v_lshrrev_b32_e32 v0, 5, v128
	s_add_u32 s88, s86, 0xc3b1000
	v_and_b32_e32 v0, 30, v0
	s_addc_u32 s89, s87, 0
	v_lshl_add_u32 v132, s2, 4, v0
	s_movk_i32 s0, 0x4800
	s_barrier
	v_cmp_gt_i32_e64 s[4:5], s0, v132
	s_mov_b64 s[0:1], exec
	s_nop 0
	v_writelane_b32 v252, s4, 38
	s_nop 1
	v_writelane_b32 v252, s5, 39
	s_and_b64 s[4:5], s[0:1], s[4:5]
	s_mov_b64 exec, s[4:5]
	s_cbranch_execz .LBB0_193
	v_and_b32_e32 v9, 63, v128
	v_lshlrev_b32_e32 v0, 4, v9
	v_add_u32_e32 v1, 0x1000, v0
	v_lshlrev_b32_e32 v2, 3, v9
	v_xor_b32_e32 v3, 32, v9
	v_xor_b32_e32 v4, 16, v9
	v_xor_b32_e32 v5, 8, v9
	v_xor_b32_e32 v6, 4, v9
	v_xor_b32_e32 v7, 2, v9
	v_xor_b32_e32 v8, 1, v9
	v_lshlrev_b32_e32 v3, 2, v3
	v_lshlrev_b32_e32 v4, 2, v4
	v_lshlrev_b32_e32 v5, 2, v5
	v_lshlrev_b32_e32 v6, 2, v6
	v_lshlrev_b32_e32 v7, 2, v7
	v_lshlrev_b32_e32 v8, 2, v8
	v_readfirstlane_b32 s10, v132
	s_lshl_b32 s12, s22, 4
	s_add_u32 s6, s86, 0x1900000
	s_addc_u32 s7, s87, 0
	s_add_u32 s100, s64, 0x0
	s_addc_u32 s101, s65, 0
	global_load_dwordx4 v[80:83], v0, s[100:101]
	global_load_dwordx4 v[84:87], v0, s[100:101] offset:1024
	global_load_dwordx4 v[88:91], v0, s[100:101] offset:2048
	global_load_dwordx4 v[92:95], v0, s[100:101] offset:3072
	s_cmp_lt_u32 s10, 0x4000
	s_cselect_b32 s98, s52, s56
	s_cselect_b32 s99, s53, s57
	s_cselect_b32 s13, 0, 0x4000
	s_sub_i32 s13, s10, s13
	s_lshl_b32 s13, s13, 12
	s_add_u32 s98, s98, s13
	s_addc_u32 s99, s99, 0
	global_load_dwordx4 v[48:51], v0, s[98:99]
	global_load_dwordx4 v[52:55], v0, s[98:99] offset:1024
	global_load_dwordx4 v[56:59], v0, s[98:99] offset:2048
	global_load_dwordx4 v[60:63], v0, s[98:99] offset:3072
	global_load_dwordx4 v[64:67], v1, s[98:99]
	global_load_dwordx4 v[68:71], v1, s[98:99] offset:1024
	global_load_dwordx4 v[72:75], v1, s[98:99] offset:2048
	global_load_dwordx4 v[76:79], v1, s[98:99] offset:3072
	s_waitcnt vmcnt(0)
.Lnorm1_loop:
	s_lshr_b32 s13, s10, 11
	s_cmp_lt_u32 s10, 0x4000
	s_cselect_b32 s13, s13, 8
	s_mul_i32 s13, s13, 0x6000
	s_add_u32 s14, s6, s13
	s_addc_u32 s15, s7, 0
	global_load_dwordx4 v[96:99], v0, s[14:15]
	global_load_dwordx4 v[100:103], v0, s[14:15] offset:1024
	global_load_dwordx4 v[104:107], v0, s[14:15] offset:2048
	global_load_dwordx4 v[108:111], v0, s[14:15] offset:3072
	global_load_dwordx4 v[112:115], v1, s[14:15]
	global_load_dwordx4 v[116:119], v1, s[14:15] offset:1024
	global_load_dwordx4 v[120:123], v1, s[14:15] offset:2048
	global_load_dwordx4 v[124:127], v1, s[14:15] offset:3072
	s_lshl_b32 s13, s10, 11
	s_add_u32 s8, s88, s13
	s_addc_u32 s9, s89, 0
	s_add_i32 s11, s10, s12
	s_cmp_lt_i32 s11, 0x4800
	s_cbranch_scc0 .Lnorm1_nopf
	s_cmp_lt_u32 s11, 0x4000
	s_cselect_b32 s98, s52, s56
	s_cselect_b32 s99, s53, s57
	s_cselect_b32 s13, 0, 0x4000
	s_sub_i32 s13, s11, s13
	s_lshl_b32 s13, s13, 12
	s_add_u32 s98, s98, s13
	s_addc_u32 s99, s99, 0
	global_load_dwordx4 v[16:19], v0, s[98:99]
	global_load_dwordx4 v[20:23], v0, s[98:99] offset:1024
	global_load_dwordx4 v[24:27], v0, s[98:99] offset:2048
	global_load_dwordx4 v[28:31], v0, s[98:99] offset:3072
	global_load_dwordx4 v[32:35], v1, s[98:99]
	global_load_dwordx4 v[36:39], v1, s[98:99] offset:1024
	global_load_dwordx4 v[40:43], v1, s[98:99] offset:2048
	global_load_dwordx4 v[44:47], v1, s[98:99] offset:3072
.Lnorm1_nopf:
	v_mul_f32_e32 v9, v48, v48
	v_mul_f32_e32 v10, v64, v64
	v_mul_f32_e32 v11, v56, v56
	v_mul_f32_e32 v12, v72, v72
	v_fmac_f32_e32 v9, v49, v49
	v_fmac_f32_e32 v10, v65, v65
	v_fmac_f32_e32 v11, v57, v57
	v_fmac_f32_e32 v12, v73, v73
	v_fmac_f32_e32 v9, v50, v50
	v_fmac_f32_e32 v10, v66, v66
	v_fmac_f32_e32 v11, v58, v58
	v_fmac_f32_e32 v12, v74, v74
	v_fmac_f32_e32 v9, v51, v51
	v_fmac_f32_e32 v10, v67, v67
	v_fmac_f32_e32 v11, v59, v59
	v_fmac_f32_e32 v12, v75, v75
	v_fmac_f32_e32 v9, v52, v52
	v_fmac_f32_e32 v10, v68, v68
	v_fmac_f32_e32 v11, v60, v60
	v_fmac_f32_e32 v12, v76, v76
	v_fmac_f32_e32 v9, v53, v53
	v_fmac_f32_e32 v10, v69, v69
	v_fmac_f32_e32 v11, v61, v61
	v_fmac_f32_e32 v12, v77, v77
	v_fmac_f32_e32 v9, v54, v54
	v_fmac_f32_e32 v10, v70, v70
	v_fmac_f32_e32 v11, v62, v62
	v_fmac_f32_e32 v12, v78, v78
	v_fmac_f32_e32 v9, v55, v55
	v_fmac_f32_e32 v10, v71, v71
	v_fmac_f32_e32 v11, v63, v63
	v_fmac_f32_e32 v12, v79, v79
	v_add_f32_e32 v9, v9, v11
	v_add_f32_e32 v10, v10, v12
	ds_bpermute_b32 v11, v3, v9
	ds_bpermute_b32 v12, v3, v10
	s_waitcnt lgkmcnt(0)
	v_add_f32_e32 v9, v9, v11
	v_add_f32_e32 v10, v10, v12
	ds_bpermute_b32 v11, v4, v9
	ds_bpermute_b32 v12, v4, v10
	s_waitcnt lgkmcnt(0)
	v_add_f32_e32 v9, v9, v11
	v_add_f32_e32 v10, v10, v12
	ds_bpermute_b32 v11, v5, v9
	ds_bpermute_b32 v12, v5, v10
	s_waitcnt lgkmcnt(0)
	v_add_f32_e32 v9, v9, v11
	v_add_f32_e32 v10, v10, v12
	ds_bpermute_b32 v11, v6, v9
	ds_bpermute_b32 v12, v6, v10
	s_waitcnt lgkmcnt(0)
	v_add_f32_e32 v9, v9, v11
	v_add_f32_e32 v10, v10, v12
	ds_bpermute_b32 v11, v7, v9
	ds_bpermute_b32 v12, v7, v10
	s_waitcnt lgkmcnt(0)
	v_add_f32_e32 v9, v9, v11
	v_add_f32_e32 v10, v10, v12
	ds_bpermute_b32 v11, v8, v9
	ds_bpermute_b32 v12, v8, v10
	s_waitcnt lgkmcnt(0)
	v_add_f32_e32 v9, v9, v11
	v_add_f32_e32 v10, v10, v12
	v_mov_b32_e32 v13, 0x358637bd
	s_mov_b32 s13, 0x800000
	v_fmamk_f32 v9, v9, 0x3a800000, v13
	v_mul_f32_e32 v11, 0x4b800000, v9
	v_cmp_gt_f32_e32 vcc, s13, v9
	s_nop 1
	v_cndmask_b32_e32 v9, v9, v11, vcc
	v_rsq_f32_e32 v9, v9
	s_nop 0
	v_mul_f32_e32 v11, 0x45800000, v9
	v_cndmask_b32_e32 v9, v9, v11, vcc
	v_fmamk_f32 v10, v10, 0x3a800000, v13
	v_mul_f32_e32 v11, 0x4b800000, v10
	v_cmp_gt_f32_e32 vcc, s13, v10
	s_nop 1
	v_cndmask_b32_e32 v10, v10, v11, vcc
	v_rsq_f32_e32 v10, v10
	s_nop 0
	v_mul_f32_e32 v11, 0x45800000, v10
	v_cndmask_b32_e32 v10, v10, v11, vcc
	s_cmp_lt_i32 s11, 0x4800
	s_cbranch_scc0 .Lnorm1_w0
	s_waitcnt vmcnt(8)
	s_branch .Lnorm1_wj

.Lnorm1_wj:
	v_add_f32_e32 v112, 1.0, v112
	v_add_f32_e32 v113, 1.0, v113
	v_add_f32_e32 v114, 1.0, v114
	v_add_f32_e32 v115, 1.0, v115
	v_mul_f32_e32 v48, v48, v9
	v_mul_f32_e32 v49, v49, v9
	v_mul_f32_e32 v50, v50, v9
	v_mul_f32_e32 v51, v51, v9
	v_mul_f32_e32 v48, v80, v48
	v_mul_f32_e32 v49, v81, v49
	v_mul_f32_e32 v50, v82, v50
	v_mul_f32_e32 v51, v83, v51
	v_fma_f32 v48, v112, v48, v96
	v_fma_f32 v49, v113, v49, v97
	v_fma_f32 v50, v114, v50, v98
	v_fma_f32 v51, v115, v51, v99
	v_cvt_pk_bf16_f32 v14, v48, v49
	v_cvt_pk_bf16_f32 v15, v50, v51
	global_store_dwordx2 v2, v[14:15], s[8:9]
	v_mul_f32_e32 v64, v64, v10
	v_mul_f32_e32 v65, v65, v10
	v_mul_f32_e32 v66, v66, v10
	v_mul_f32_e32 v67, v67, v10
	v_mul_f32_e32 v64, v80, v64
	v_mul_f32_e32 v65, v81, v65
	v_mul_f32_e32 v66, v82, v66
	v_mul_f32_e32 v67, v83, v67
	v_fma_f32 v64, v112, v64, v96
	v_fma_f32 v65, v113, v65, v97
	v_fma_f32 v66, v114, v66, v98
	v_fma_f32 v67, v115, v67, v99
	v_cvt_pk_bf16_f32 v12, v64, v65
	v_cvt_pk_bf16_f32 v13, v66, v67
	global_store_dwordx2 v2, v[12:13], s[8:9] offset:2048
	v_add_f32_e32 v116, 1.0, v116
	v_add_f32_e32 v117, 1.0, v117
	v_add_f32_e32 v118, 1.0, v118
	v_add_f32_e32 v119, 1.0, v119
	v_mul_f32_e32 v52, v52, v9
	v_mul_f32_e32 v53, v53, v9
	v_mul_f32_e32 v54, v54, v9
	v_mul_f32_e32 v55, v55, v9
	v_mul_f32_e32 v52, v84, v52
	v_mul_f32_e32 v53, v85, v53
	v_mul_f32_e32 v54, v86, v54
	v_mul_f32_e32 v55, v87, v55
	v_fma_f32 v52, v116, v52, v100
	v_fma_f32 v53, v117, v53, v101
	v_fma_f32 v54, v118, v54, v102
	v_fma_f32 v55, v119, v55, v103
	v_cvt_pk_bf16_f32 v14, v52, v53
	v_cvt_pk_bf16_f32 v15, v54, v55
	global_store_dwordx2 v2, v[14:15], s[8:9] offset:512
	v_mul_f32_e32 v68, v68, v10
	v_mul_f32_e32 v69, v69, v10
	v_mul_f32_e32 v70, v70, v10
	v_mul_f32_e32 v71, v71, v10
	v_mul_f32_e32 v68, v84, v68
	v_mul_f32_e32 v69, v85, v69
	v_mul_f32_e32 v70, v86, v70
	v_mul_f32_e32 v71, v87, v71
	v_fma_f32 v68, v116, v68, v100
	v_fma_f32 v69, v117, v69, v101
	v_fma_f32 v70, v118, v70, v102
	v_fma_f32 v71, v119, v71, v103
	v_cvt_pk_bf16_f32 v12, v68, v69
	v_cvt_pk_bf16_f32 v13, v70, v71
	global_store_dwordx2 v2, v[12:13], s[8:9] offset:2560
	v_add_f32_e32 v120, 1.0, v120
	v_add_f32_e32 v121, 1.0, v121
	v_add_f32_e32 v122, 1.0, v122
	v_add_f32_e32 v123, 1.0, v123
	v_mul_f32_e32 v56, v56, v9
	v_mul_f32_e32 v57, v57, v9
	v_mul_f32_e32 v58, v58, v9
	v_mul_f32_e32 v59, v59, v9
	v_mul_f32_e32 v56, v88, v56
	v_mul_f32_e32 v57, v89, v57
	v_mul_f32_e32 v58, v90, v58
	v_mul_f32_e32 v59, v91, v59
	v_fma_f32 v56, v120, v56, v104
	v_fma_f32 v57, v121, v57, v105
	v_fma_f32 v58, v122, v58, v106
	v_fma_f32 v59, v123, v59, v107
	v_cvt_pk_bf16_f32 v14, v56, v57
	v_cvt_pk_bf16_f32 v15, v58, v59
	global_store_dwordx2 v2, v[14:15], s[8:9] offset:1024
	v_mul_f32_e32 v72, v72, v10
	v_mul_f32_e32 v73, v73, v10
	v_mul_f32_e32 v74, v74, v10
	v_mul_f32_e32 v75, v75, v10
	v_mul_f32_e32 v72, v88, v72
	v_mul_f32_e32 v73, v89, v73
	v_mul_f32_e32 v74, v90, v74
	v_mul_f32_e32 v75, v91, v75
	v_fma_f32 v72, v120, v72, v104
	v_fma_f32 v73, v121, v73, v105
	v_fma_f32 v74, v122, v74, v106
	v_fma_f32 v75, v123, v75, v107
	v_cvt_pk_bf16_f32 v12, v72, v73
	v_cvt_pk_bf16_f32 v13, v74, v75
	global_store_dwordx2 v2, v[12:13], s[8:9] offset:3072
	v_add_f32_e32 v124, 1.0, v124
	v_add_f32_e32 v125, 1.0, v125
	v_add_f32_e32 v126, 1.0, v126
	v_add_f32_e32 v127, 1.0, v127
	v_mul_f32_e32 v60, v60, v9
	v_mul_f32_e32 v61, v61, v9
	v_mul_f32_e32 v62, v62, v9
	v_mul_f32_e32 v63, v63, v9
	v_mul_f32_e32 v60, v92, v60
	v_mul_f32_e32 v61, v93, v61
	v_mul_f32_e32 v62, v94, v62
	v_mul_f32_e32 v63, v95, v63
	v_fma_f32 v60, v124, v60, v108
	v_fma_f32 v61, v125, v61, v109
	v_fma_f32 v62, v126, v62, v110
	v_fma_f32 v63, v127, v63, v111
	v_cvt_pk_bf16_f32 v14, v60, v61
	v_cvt_pk_bf16_f32 v15, v62, v63
	global_store_dwordx2 v2, v[14:15], s[8:9] offset:1536
	v_mul_f32_e32 v76, v76, v10
	v_mul_f32_e32 v77, v77, v10
	v_mul_f32_e32 v78, v78, v10
	v_mul_f32_e32 v79, v79, v10
	v_mul_f32_e32 v76, v92, v76
	v_mul_f32_e32 v77, v93, v77
	v_mul_f32_e32 v78, v94, v78
	v_mul_f32_e32 v79, v95, v79
	v_fma_f32 v76, v124, v76, v108
	v_fma_f32 v77, v125, v77, v109
	v_fma_f32 v78, v126, v78, v110
	v_fma_f32 v79, v127, v79, v111
	v_cvt_pk_bf16_f32 v12, v76, v77
	v_cvt_pk_bf16_f32 v13, v78, v79
	global_store_dwordx2 v2, v[12:13], s[8:9] offset:3584
	s_cmp_lt_i32 s11, 0x4800
	s_cbranch_scc0 .LBB0_193
	s_waitcnt vmcnt(8)
	v_mov_b64_e32 v[48:49], v[16:17]
	v_mov_b64_e32 v[50:51], v[18:19]
	v_mov_b64_e32 v[52:53], v[20:21]
	v_mov_b64_e32 v[54:55], v[22:23]
	v_mov_b64_e32 v[56:57], v[24:25]
	v_mov_b64_e32 v[58:59], v[26:27]
	v_mov_b64_e32 v[60:61], v[28:29]
	v_mov_b64_e32 v[62:63], v[30:31]
	v_mov_b64_e32 v[64:65], v[32:33]
	v_mov_b64_e32 v[66:67], v[34:35]
	v_mov_b64_e32 v[68:69], v[36:37]
	v_mov_b64_e32 v[70:71], v[38:39]
	v_mov_b64_e32 v[72:73], v[40:41]
	v_mov_b64_e32 v[74:75], v[42:43]
	v_mov_b64_e32 v[76:77], v[44:45]
	v_mov_b64_e32 v[78:79], v[46:47]
	s_mov_b32 s10, s11
	s_branch .Lnorm1_loop

.LBB0_926:
	s_or_b64 exec, exec, s[0:1]
	s_waitcnt lgkmcnt(0)
	s_barrier
	s_mov_b64 s[0:1], exec
	v_readlane_b32 s4, v252, 38
	v_readlane_b32 s5, v252, 39
	s_and_b64 s[4:5], s[0:1], s[4:5]
	s_mov_b64 exec, s[4:5]
	s_cbranch_execz .LBB0_937
	v_and_b32_e32 v9, 63, v128
	v_lshlrev_b32_e32 v0, 4, v9
	v_add_u32_e32 v1, 0x1000, v0
	v_lshlrev_b32_e32 v2, 3, v9
	v_xor_b32_e32 v3, 32, v9
	v_xor_b32_e32 v4, 16, v9
	v_xor_b32_e32 v5, 8, v9
	v_xor_b32_e32 v6, 4, v9
	v_xor_b32_e32 v7, 2, v9
	v_xor_b32_e32 v8, 1, v9
	v_lshlrev_b32_e32 v3, 2, v3
	v_lshlrev_b32_e32 v4, 2, v4
	v_lshlrev_b32_e32 v5, 2, v5
	v_lshlrev_b32_e32 v6, 2, v6
	v_lshlrev_b32_e32 v7, 2, v7
	v_lshlrev_b32_e32 v8, 2, v8
	v_readfirstlane_b32 s10, v132
	s_lshl_b32 s12, s22, 4
	s_add_u32 s6, s86, 0x1903000
	s_addc_u32 s7, s87, 0
	s_add_u32 s100, s66, 0x0
	s_addc_u32 s101, s67, 0
	global_load_dwordx4 v[80:83], v0, s[100:101]
	global_load_dwordx4 v[84:87], v0, s[100:101] offset:1024
	global_load_dwordx4 v[88:91], v0, s[100:101] offset:2048
	global_load_dwordx4 v[92:95], v0, s[100:101] offset:3072
	s_cmp_lt_u32 s10, 0x4000
	s_cselect_b32 s98, s84, s70
	s_cselect_b32 s99, s85, s71
	s_cselect_b32 s13, 0, 0x4000
	s_sub_i32 s13, s10, s13
	s_lshl_b32 s13, s13, 12
	s_add_u32 s98, s98, s13
	s_addc_u32 s99, s99, 0
	global_load_dwordx4 v[48:51], v0, s[98:99]
	global_load_dwordx4 v[52:55], v0, s[98:99] offset:1024
	global_load_dwordx4 v[56:59], v0, s[98:99] offset:2048
	global_load_dwordx4 v[60:63], v0, s[98:99] offset:3072
	global_load_dwordx4 v[64:67], v1, s[98:99]
	global_load_dwordx4 v[68:71], v1, s[98:99] offset:1024
	global_load_dwordx4 v[72:75], v1, s[98:99] offset:2048
	global_load_dwordx4 v[76:79], v1, s[98:99] offset:3072
	s_waitcnt vmcnt(0)
.Lnorm2_loop:
	s_lshr_b32 s13, s10, 11
	s_cmp_lt_u32 s10, 0x4000
	s_cselect_b32 s13, s13, 8
	s_mul_i32 s13, s13, 0x6000
	s_add_u32 s14, s6, s13
	s_addc_u32 s15, s7, 0
	global_load_dwordx4 v[96:99], v0, s[14:15]
	global_load_dwordx4 v[100:103], v0, s[14:15] offset:1024
	global_load_dwordx4 v[104:107], v0, s[14:15] offset:2048
	global_load_dwordx4 v[108:111], v0, s[14:15] offset:3072
	global_load_dwordx4 v[112:115], v1, s[14:15]
	global_load_dwordx4 v[116:119], v1, s[14:15] offset:1024
	global_load_dwordx4 v[120:123], v1, s[14:15] offset:2048
	global_load_dwordx4 v[124:127], v1, s[14:15] offset:3072
	s_lshl_b32 s13, s10, 11
	s_add_u32 s8, s88, s13
	s_addc_u32 s9, s89, 0
	s_add_i32 s11, s10, s12
	s_cmp_lt_i32 s11, 0x4800
	s_cbranch_scc0 .Lnorm2_nopf
	s_cmp_lt_u32 s11, 0x4000
	s_cselect_b32 s98, s84, s70
	s_cselect_b32 s99, s85, s71
	s_cselect_b32 s13, 0, 0x4000
	s_sub_i32 s13, s11, s13
	s_lshl_b32 s13, s13, 12
	s_add_u32 s98, s98, s13
	s_addc_u32 s99, s99, 0
	global_load_dwordx4 v[16:19], v0, s[98:99]
	global_load_dwordx4 v[20:23], v0, s[98:99] offset:1024
	global_load_dwordx4 v[24:27], v0, s[98:99] offset:2048
	global_load_dwordx4 v[28:31], v0, s[98:99] offset:3072
	global_load_dwordx4 v[32:35], v1, s[98:99]
	global_load_dwordx4 v[36:39], v1, s[98:99] offset:1024
	global_load_dwordx4 v[40:43], v1, s[98:99] offset:2048
	global_load_dwordx4 v[44:47], v1, s[98:99] offset:3072

.LBB0_1391:
	s_or_b64 exec, exec, s[0:1]
	s_waitcnt lgkmcnt(0)
	s_barrier
	s_mov_b64 s[0:1], exec
	v_readlane_b32 s6, v252, 38
	v_readlane_b32 s7, v252, 39
	s_and_b64 s[6:7], s[0:1], s[6:7]
	s_mov_b64 exec, s[6:7]
	s_cbranch_execz .LBB0_1402
	v_and_b32_e32 v9, 63, v128
	v_lshlrev_b32_e32 v0, 4, v9
	v_add_u32_e32 v1, 0x1000, v0
	v_lshlrev_b32_e32 v2, 3, v9
	v_xor_b32_e32 v3, 32, v9
	v_xor_b32_e32 v4, 16, v9
	v_xor_b32_e32 v5, 8, v9
	v_xor_b32_e32 v6, 4, v9
	v_xor_b32_e32 v7, 2, v9
	v_xor_b32_e32 v8, 1, v9
	v_lshlrev_b32_e32 v3, 2, v3
	v_lshlrev_b32_e32 v4, 2, v4
	v_lshlrev_b32_e32 v5, 2, v5
	v_lshlrev_b32_e32 v6, 2, v6
	v_lshlrev_b32_e32 v7, 2, v7
	v_lshlrev_b32_e32 v8, 2, v8
	v_readfirstlane_b32 s10, v132
	s_lshl_b32 s12, s22, 4
	s_add_u32 s6, s86, 0x1936000
	s_addc_u32 s7, s87, 0
	s_add_u32 s100, s64, 0x1000
	s_addc_u32 s101, s65, 0
	global_load_dwordx4 v[80:83], v0, s[100:101]
	global_load_dwordx4 v[84:87], v0, s[100:101] offset:1024
	global_load_dwordx4 v[88:91], v0, s[100:101] offset:2048
	global_load_dwordx4 v[92:95], v0, s[100:101] offset:3072
	s_cmp_lt_u32 s10, 0x4000
	s_cselect_b32 s98, s84, s70
	s_cselect_b32 s99, s85, s71
	s_cselect_b32 s13, 0, 0x4000
	s_sub_i32 s13, s10, s13
	s_lshl_b32 s13, s13, 12
	s_add_u32 s98, s98, s13
	s_addc_u32 s99, s99, 0
	global_load_dwordx4 v[48:51], v0, s[98:99]
	global_load_dwordx4 v[52:55], v0, s[98:99] offset:1024
	global_load_dwordx4 v[56:59], v0, s[98:99] offset:2048
	global_load_dwordx4 v[60:63], v0, s[98:99] offset:3072
	global_load_dwordx4 v[64:67], v1, s[98:99]
	global_load_dwordx4 v[68:71], v1, s[98:99] offset:1024
	global_load_dwordx4 v[72:75], v1, s[98:99] offset:2048
	global_load_dwordx4 v[76:79], v1, s[98:99] offset:3072
	s_waitcnt vmcnt(0)

.LBB0_1926:
	s_or_b64 exec, exec, s[0:1]
	s_movk_i32 s0, 0x4000
	v_cmp_gt_i32_e32 vcc, s0, v132
	s_waitcnt lgkmcnt(0)
	s_barrier
	s_and_saveexec_b64 s[0:1], vcc
	s_cbranch_execz .LBB0_1933
	v_and_b32_e32 v9, 63, v128
	v_lshlrev_b32_e32 v0, 4, v9
	v_add_u32_e32 v1, 0x1000, v0
	v_lshlrev_b32_e32 v2, 3, v9
	v_xor_b32_e32 v3, 32, v9
	v_xor_b32_e32 v4, 16, v9
	v_xor_b32_e32 v5, 8, v9
	v_xor_b32_e32 v6, 4, v9
	v_xor_b32_e32 v7, 2, v9
	v_xor_b32_e32 v8, 1, v9
	v_lshlrev_b32_e32 v3, 2, v3
	v_lshlrev_b32_e32 v4, 2, v4
	v_lshlrev_b32_e32 v5, 2, v5
	v_lshlrev_b32_e32 v6, 2, v6
	v_lshlrev_b32_e32 v7, 2, v7
	v_lshlrev_b32_e32 v8, 2, v8
	v_readfirstlane_b32 s10, v132
	s_lshl_b32 s12, s22, 4
	s_add_u32 s6, s86, 0x1939000
	s_addc_u32 s7, s87, 0
	s_add_u32 s100, s66, 0x1000
	s_addc_u32 s101, s67, 0
	global_load_dwordx4 v[80:83], v0, s[100:101]
	global_load_dwordx4 v[84:87], v0, s[100:101] offset:1024
	global_load_dwordx4 v[88:91], v0, s[100:101] offset:2048
	global_load_dwordx4 v[92:95], v0, s[100:101] offset:3072
	s_cmp_lt_u32 s10, 0x4000
	s_cselect_b32 s98, s84, s70
	s_cselect_b32 s99, s85, s71
	s_cselect_b32 s13, 0, 0x4000
	s_sub_i32 s13, s10, s13
	s_lshl_b32 s13, s13, 12
	s_add_u32 s98, s98, s13
	s_addc_u32 s99, s99, 0
	global_load_dwordx4 v[48:51], v0, s[98:99]
	global_load_dwordx4 v[52:55], v0, s[98:99] offset:1024
	global_load_dwordx4 v[56:59], v0, s[98:99] offset:2048
	global_load_dwordx4 v[60:63], v0, s[98:99] offset:3072
	global_load_dwordx4 v[64:67], v1, s[98:99]
	global_load_dwordx4 v[68:71], v1, s[98:99] offset:1024
	global_load_dwordx4 v[72:75], v1, s[98:99] offset:2048
	global_load_dwordx4 v[76:79], v1, s[98:99] offset:3072
	s_waitcnt vmcnt(0)
.Lnorm4_loop:
	s_lshr_b32 s13, s10, 11
	s_cmp_lt_u32 s10, 0x4000
	s_cselect_b32 s13, s13, 8
	s_mul_i32 s13, s13, 0x6000
	s_add_u32 s14, s6, s13
	s_addc_u32 s15, s7, 0
	global_load_dwordx4 v[96:99], v0, s[14:15]
	global_load_dwordx4 v[100:103], v0, s[14:15] offset:1024
	global_load_dwordx4 v[104:107], v0, s[14:15] offset:2048
	global_load_dwordx4 v[108:111], v0, s[14:15] offset:3072
	global_load_dwordx4 v[112:115], v1, s[14:15]
	global_load_dwordx4 v[116:119], v1, s[14:15] offset:1024
	global_load_dwordx4 v[120:123], v1, s[14:15] offset:2048
	global_load_dwordx4 v[124:127], v1, s[14:15] offset:3072
	s_lshl_b32 s13, s10, 11
	s_add_u32 s8, s88, s13
	s_addc_u32 s9, s89, 0
	s_add_i32 s11, s10, s12
	s_cmp_lt_i32 s11, 0x4000
	s_cbranch_scc0 .Lnorm4_nopf
	s_cmp_lt_u32 s11, 0x4000
	s_cselect_b32 s98, s84, s70
	s_cselect_b32 s99, s85, s71
	s_cselect_b32 s13, 0, 0x4000
	s_sub_i32 s13, s11, s13
	s_lshl_b32 s13, s13, 12
	s_add_u32 s98, s98, s13
	s_addc_u32 s99, s99, 0
	global_load_dwordx4 v[16:19], v0, s[98:99]
	global_load_dwordx4 v[20:23], v0, s[98:99] offset:1024
	global_load_dwordx4 v[24:27], v0, s[98:99] offset:2048
	global_load_dwordx4 v[28:31], v0, s[98:99] offset:3072
	global_load_dwordx4 v[32:35], v1, s[98:99]
	global_load_dwordx4 v[36:39], v1, s[98:99] offset:1024
	global_load_dwordx4 v[40:43], v1, s[98:99] offset:2048
	global_load_dwordx4 v[44:47], v1, s[98:99] offset:3072
.Lnorm4_nopf:
	v_mul_f32_e32 v9, v48, v48
	v_mul_f32_e32 v10, v64, v64
	v_mul_f32_e32 v11, v56, v56
	v_mul_f32_e32 v12, v72, v72
	v_fmac_f32_e32 v9, v49, v49
	v_fmac_f32_e32 v10, v65, v65
	v_fmac_f32_e32 v11, v57, v57
	v_fmac_f32_e32 v12, v73, v73
	v_fmac_f32_e32 v9, v50, v50
	v_fmac_f32_e32 v10, v66, v66
	v_fmac_f32_e32 v11, v58, v58
	v_fmac_f32_e32 v12, v74, v74
	v_fmac_f32_e32 v9, v51, v51
	v_fmac_f32_e32 v10, v67, v67
	v_fmac_f32_e32 v11, v59, v59
	v_fmac_f32_e32 v12, v75, v75
	v_fmac_f32_e32 v9, v52, v52
	v_fmac_f32_e32 v10, v68, v68
	v_fmac_f32_e32 v11, v60, v60
	v_fmac_f32_e32 v12, v76, v76
	v_fmac_f32_e32 v9, v53, v53
	v_fmac_f32_e32 v10, v69, v69
	v_fmac_f32_e32 v11, v61, v61
	v_fmac_f32_e32 v12, v77, v77
	v_fmac_f32_e32 v9, v54, v54
	v_fmac_f32_e32 v10, v70, v70
	v_fmac_f32_e32 v11, v62, v62
	v_fmac_f32_e32 v12, v78, v78
	v_fmac_f32_e32 v9, v55, v55
	v_fmac_f32_e32 v10, v71, v71
	v_fmac_f32_e32 v11, v63, v63
	v_fmac_f32_e32 v12, v79, v79
	v_add_f32_e32 v9, v9, v11
	v_add_f32_e32 v10, v10, v12
	ds_bpermute_b32 v11, v3, v9
	ds_bpermute_b32 v12, v3, v10
	s_waitcnt lgkmcnt(0)
	v_add_f32_e32 v9, v9, v11
	v_add_f32_e32 v10, v10, v12
	ds_bpermute_b32 v11, v4, v9
	ds_bpermute_b32 v12, v4, v10
	s_waitcnt lgkmcnt(0)
	v_add_f32_e32 v9, v9, v11
	v_add_f32_e32 v10, v10, v12
	ds_bpermute_b32 v11, v5, v9
	ds_bpermute_b32 v12, v5, v10
	s_waitcnt lgkmcnt(0)
	v_add_f32_e32 v9, v9, v11
	v_add_f32_e32 v10, v10, v12
	ds_bpermute_b32 v11, v6, v9
	ds_bpermute_b32 v12, v6, v10
	s_waitcnt lgkmcnt(0)
	v_add_f32_e32 v9, v9, v11
	v_add_f32_e32 v10, v10, v12
	ds_bpermute_b32 v11, v7, v9
	ds_bpermute_b32 v12, v7, v10
	s_waitcnt lgkmcnt(0)
	v_add_f32_e32 v9, v9, v11
	v_add_f32_e32 v10, v10, v12
	ds_bpermute_b32 v11, v8, v9
	ds_bpermute_b32 v12, v8, v10
	s_waitcnt lgkmcnt(0)
	v_add_f32_e32 v9, v9, v11
	v_add_f32_e32 v10, v10, v12
	v_mov_b32_e32 v13, 0x358637bd
	s_mov_b32 s13, 0x800000
	v_fmamk_f32 v9, v9, 0x3a800000, v13
	v_mul_f32_e32 v11, 0x4b800000, v9
	v_cmp_gt_f32_e32 vcc, s13, v9
	s_nop 1
	v_cndmask_b32_e32 v9, v9, v11, vcc
	v_rsq_f32_e32 v9, v9
	s_nop 0
	v_mul_f32_e32 v11, 0x45800000, v9
	v_cndmask_b32_e32 v9, v9, v11, vcc
	v_fmamk_f32 v10, v10, 0x3a800000, v13
	v_mul_f32_e32 v11, 0x4b800000, v10
	v_cmp_gt_f32_e32 vcc, s13, v10
	s_nop 1
	v_cndmask_b32_e32 v10, v10, v11, vcc
	v_rsq_f32_e32 v10, v10
	s_nop 0
	v_mul_f32_e32 v11, 0x45800000, v10
	v_cndmask_b32_e32 v10, v10, v11, vcc
	s_cmp_lt_i32 s11, 0x4000
	s_cbranch_scc0 .Lnorm4_w0
	s_waitcnt vmcnt(8)
	s_branch .Lnorm4_wj

.Lnorm4_wj:
	v_add_f32_e32 v112, 1.0, v112
	v_add_f32_e32 v113, 1.0, v113
	v_add_f32_e32 v114, 1.0, v114
	v_add_f32_e32 v115, 1.0, v115
	v_mul_f32_e32 v48, v48, v9
	v_mul_f32_e32 v49, v49, v9
	v_mul_f32_e32 v50, v50, v9
	v_mul_f32_e32 v51, v51, v9
	v_mul_f32_e32 v48, v80, v48
	v_mul_f32_e32 v49, v81, v49
	v_mul_f32_e32 v50, v82, v50
	v_mul_f32_e32 v51, v83, v51
	v_fma_f32 v48, v112, v48, v96
	v_fma_f32 v49, v113, v49, v97
	v_fma_f32 v50, v114, v50, v98
	v_fma_f32 v51, v115, v51, v99
	v_cvt_pk_bf16_f32 v14, v48, v49
	v_cvt_pk_bf16_f32 v15, v50, v51
	global_store_dwordx2 v2, v[14:15], s[8:9]
	v_mul_f32_e32 v64, v64, v10
	v_mul_f32_e32 v65, v65, v10
	v_mul_f32_e32 v66, v66, v10
	v_mul_f32_e32 v67, v67, v10
	v_mul_f32_e32 v64, v80, v64
	v_mul_f32_e32 v65, v81, v65
	v_mul_f32_e32 v66, v82, v66
	v_mul_f32_e32 v67, v83, v67
	v_fma_f32 v64, v112, v64, v96
	v_fma_f32 v65, v113, v65, v97
	v_fma_f32 v66, v114, v66, v98
	v_fma_f32 v67, v115, v67, v99
	v_cvt_pk_bf16_f32 v12, v64, v65
	v_cvt_pk_bf16_f32 v13, v66, v67
	global_store_dwordx2 v2, v[12:13], s[8:9] offset:2048
	v_add_f32_e32 v116, 1.0, v116
	v_add_f32_e32 v117, 1.0, v117
	v_add_f32_e32 v118, 1.0, v118
	v_add_f32_e32 v119, 1.0, v119
	v_mul_f32_e32 v52, v52, v9
	v_mul_f32_e32 v53, v53, v9
	v_mul_f32_e32 v54, v54, v9
	v_mul_f32_e32 v55, v55, v9
	v_mul_f32_e32 v52, v84, v52
	v_mul_f32_e32 v53, v85, v53
	v_mul_f32_e32 v54, v86, v54
	v_mul_f32_e32 v55, v87, v55
	v_fma_f32 v52, v116, v52, v100
	v_fma_f32 v53, v117, v53, v101
	v_fma_f32 v54, v118, v54, v102
	v_fma_f32 v55, v119, v55, v103
	v_cvt_pk_bf16_f32 v14, v52, v53
	v_cvt_pk_bf16_f32 v15, v54, v55
	global_store_dwordx2 v2, v[14:15], s[8:9] offset:512
	v_mul_f32_e32 v68, v68, v10
	v_mul_f32_e32 v69, v69, v10
	v_mul_f32_e32 v70, v70, v10
	v_mul_f32_e32 v71, v71, v10
	v_mul_f32_e32 v68, v84, v68
	v_mul_f32_e32 v69, v85, v69
	v_mul_f32_e32 v70, v86, v70
	v_mul_f32_e32 v71, v87, v71
	v_fma_f32 v68, v116, v68, v100
	v_fma_f32 v69, v117, v69, v101
	v_fma_f32 v70, v118, v70, v102
	v_fma_f32 v71, v119, v71, v103
	v_cvt_pk_bf16_f32 v12, v68, v69
	v_cvt_pk_bf16_f32 v13, v70, v71
	global_store_dwordx2 v2, v[12:13], s[8:9] offset:2560
	v_add_f32_e32 v120, 1.0, v120
	v_add_f32_e32 v121, 1.0, v121
	v_add_f32_e32 v122, 1.0, v122
	v_add_f32_e32 v123, 1.0, v123
	v_mul_f32_e32 v56, v56, v9
	v_mul_f32_e32 v57, v57, v9
	v_mul_f32_e32 v58, v58, v9
	v_mul_f32_e32 v59, v59, v9
	v_mul_f32_e32 v56, v88, v56
	v_mul_f32_e32 v57, v89, v57
	v_mul_f32_e32 v58, v90, v58
	v_mul_f32_e32 v59, v91, v59
	v_fma_f32 v56, v120, v56, v104
	v_fma_f32 v57, v121, v57, v105
	v_fma_f32 v58, v122, v58, v106
	v_fma_f32 v59, v123, v59, v107
	v_cvt_pk_bf16_f32 v14, v56, v57
	v_cvt_pk_bf16_f32 v15, v58, v59
	global_store_dwordx2 v2, v[14:15], s[8:9] offset:1024
	v_mul_f32_e32 v72, v72, v10
	v_mul_f32_e32 v73, v73, v10
	v_mul_f32_e32 v74, v74, v10
	v_mul_f32_e32 v75, v75, v10
	v_mul_f32_e32 v72, v88, v72
	v_mul_f32_e32 v73, v89, v73
	v_mul_f32_e32 v74, v90, v74
	v_mul_f32_e32 v75, v91, v75
	v_fma_f32 v72, v120, v72, v104
	v_fma_f32 v73, v121, v73, v105
	v_fma_f32 v74, v122, v74, v106
	v_fma_f32 v75, v123, v75, v107
	v_cvt_pk_bf16_f32 v12, v72, v73
	v_cvt_pk_bf16_f32 v13, v74, v75
	global_store_dwordx2 v2, v[12:13], s[8:9] offset:3072
	v_add_f32_e32 v124, 1.0, v124
	v_add_f32_e32 v125, 1.0, v125
	v_add_f32_e32 v126, 1.0, v126
	v_add_f32_e32 v127, 1.0, v127
	v_mul_f32_e32 v60, v60, v9
	v_mul_f32_e32 v61, v61, v9
	v_mul_f32_e32 v62, v62, v9
	v_mul_f32_e32 v63, v63, v9
	v_mul_f32_e32 v60, v92, v60
	v_mul_f32_e32 v61, v93, v61
	v_mul_f32_e32 v62, v94, v62
	v_mul_f32_e32 v63, v95, v63
	v_fma_f32 v60, v124, v60, v108
	v_fma_f32 v61, v125, v61, v109
	v_fma_f32 v62, v126, v62, v110
	v_fma_f32 v63, v127, v63, v111
	v_cvt_pk_bf16_f32 v14, v60, v61
	v_cvt_pk_bf16_f32 v15, v62, v63
	global_store_dwordx2 v2, v[14:15], s[8:9] offset:1536
	v_mul_f32_e32 v76, v76, v10
	v_mul_f32_e32 v77, v77, v10
	v_mul_f32_e32 v78, v78, v10
	v_mul_f32_e32 v79, v79, v10
	v_mul_f32_e32 v76, v92, v76
	v_mul_f32_e32 v77, v93, v77
	v_mul_f32_e32 v78, v94, v78
	v_mul_f32_e32 v79, v95, v79
	v_fma_f32 v76, v124, v76, v108
	v_fma_f32 v77, v125, v77, v109
	v_fma_f32 v78, v126, v78, v110
	v_fma_f32 v79, v127, v79, v111
	v_cvt_pk_bf16_f32 v12, v76, v77
	v_cvt_pk_bf16_f32 v13, v78, v79
	global_store_dwordx2 v2, v[12:13], s[8:9] offset:3584
	s_cmp_lt_i32 s11, 0x4000
	s_cbranch_scc0 .LBB0_1933
	s_waitcnt vmcnt(8)
	v_mov_b64_e32 v[48:49], v[16:17]
	v_mov_b64_e32 v[50:51], v[18:19]
	v_mov_b64_e32 v[52:53], v[20:21]
	v_mov_b64_e32 v[54:55], v[22:23]
	v_mov_b64_e32 v[56:57], v[24:25]
	v_mov_b64_e32 v[58:59], v[26:27]
	v_mov_b64_e32 v[60:61], v[28:29]
	v_mov_b64_e32 v[62:63], v[30:31]
	v_mov_b64_e32 v[64:65], v[32:33]
	v_mov_b64_e32 v[66:67], v[34:35]
	v_mov_b64_e32 v[68:69], v[36:37]
	v_mov_b64_e32 v[70:71], v[38:39]
	v_mov_b64_e32 v[72:73], v[40:41]
	v_mov_b64_e32 v[74:75], v[42:43]
	v_mov_b64_e32 v[76:77], v[44:45]
	v_mov_b64_e32 v[78:79], v[46:47]
	s_mov_b32 s10, s11
	s_branch .Lnorm4_loop
